# added start staggers: P2 (CUs>=96 +12us), P5 (CUs>=176 +17us), P12 (half the CUs +12us) on top of fused P13 + P3 stagger
# baseline (speedup 1.0000x reference)
; #define PG8_WAIT_V(n) asm volatile("s_waitcnt vmcnt(" #n ")" ::: "memory")
; #define PG8_BAR __builtin_amdgcn_s_barrier()
; #define SEAM(k) do { if (IN(k) && IN((k) + 1)) { if (a.ph_hi > 4096) cg::this_grid().sync(); else xcd_barrier(xbar); } } while (0)
; template <class Epi, class Sched, bool ALIGN_EPI = false, bool SP2 = false>
; __device__ __forceinline__ void gemm_phase(PG8_LAS unsigned char* lds, const Gemm g, const Sched& S, const Epi& E) {
;     const int tid = threadIdx.x, wid = __builtin_amdgcn_readfirstlane(tid >> 6), lane = tid & 63, wr = wid >> 2, wc = wid & 3, fr = lane & 15, fq = lane >> 4;
;     const int K = g.K, nt = K / BK;
;     unsigned voffA[2], voffB[2];
; #pragma unroll
;     for (int i = 0; i < 2; ++i) { int R, C; stage_rc(tid * 16 + i * 8192, R, C); const int Rb = Epi::PERM ? ((R & ~31) + perm32(R & 31)) : R;
;         voffA[i] = (unsigned)(R * K + C) * 2u; voffB[i] = (unsigned)(Rb * K + C) * 2u; }
;     const size_t kstep = (size_t)(BK * 2);
;     const size_t hstep = (size_t)HALF * K * 2;
;     const size_t tstep = 2 * hstep;
;     const unsigned ldsw = (unsigned)wid * 1024u;
;     const int aoff = lds_byte(wr * 64 + fr, fq * 8), boff = lds_byte(wc * 32 + fr, fq * 8);
;     ...
;     Unit cur, nxt; int ui = 0;
;     if (!S.next(0, cur)) return;
;     f32x4 acc[2][2][4][2];
; #pragma unroll
;     for (int a = 0; a < 2; ++a)
; #pragma unroll
;         for (int b = 0; b < 2; ++b)
; #pragma unroll
;             for (int m = 0; m < 4; ++m)
; #pragma unroll
;                 for (int n = 0; n < 2; ++n) acc[a][b][m][n] = (f32x4){0.f, 0.f, 0.f, 0.f};
;     bf16x8 At[4][2], B0[2][2], B1[2][2];
;     const char* cA = (const char*)g.A + (size_t)cur.pm * tstep; const char* cB = (const char*)g.Bt + (size_t)cur.pn * tstep;
;     S.a_ready(cur);
;     if constexpr (SP2) {
;         PG8_STAGE(PG8_SB(0, 0), cB, voffB); PG8_STAGE(PG8_SB(0, 1), cB + hstep, voffB); PG8_STAGE(PG8_SA(0, 0), cA, voffA); PG8_STAGE(PG8_SA(0, 1), cA + hstep, voffA);
;         if (wr == 1) PG8_BAR;
;         PG8_WAIT_V(2); PG8_BAR;
; __global__ void __launch_bounds__(512, 2) fwd_kernel(Args a) {
;     ...
;     if (IN(2)) { pg8::Gemm g{XN, (const bf16_t*)(ws + WS_W1A), MALL, NFF2, D}; pg8::StaticOrder S; S.init(MALL, NFF2, G, (int)blockIdx.x); EpiSwiGLU<false> E{ZH, nullptr, nullptr};
;         pg8::gemm_phase<EpiSwiGLU<false>, pg8::StaticOrder, true, true>(ldsg, g, S, E); } SEAM(2);
.LBB0_282:
	s_cmp_ge_u32 s2, 96
	s_cselect_b32 s100, 1200, 0
	s_memrealtime s[98:99]
	s_waitcnt lgkmcnt(0)
	s_add_u32 s100, s100, s98
.Lstag_p2:
	s_sleep 8
	s_memrealtime s[98:99]
	s_waitcnt lgkmcnt(0)
	s_sub_u32 s101, s100, s98
	s_cmp_gt_i32 s101, 0
	s_cbranch_scc1 .Lstag_p2
	s_cmp_lt_i32 s90, 3
	s_cselect_b64 s[0:1], -1, 0
	s_add_u32 s56, s88, 0xc800000
	s_addc_u32 s57, s89, 0
	s_and_b64 s[0:1], s[0:1], s[4:5]
	s_andn2_b64 vcc, exec, s[0:1]
	s_cbranch_vccnz .LBB0_299
	s_cmpk_gt_i32 s2, 0x175f
	v_readfirstlane_b32 s5, v1
	s_cbranch_scc1 .LBB0_299
	v_lshrrev_b32_e32 v2, 5, v1
	s_waitcnt vmcnt(0)
	v_lshrrev_b32_e32 v4, 1, v1
	v_and_b32_e32 v2, 4, v2
	v_bfe_u32 v3, v1, 2, 2
	v_and_b32_e32 v4, 24, v4
	v_or3_b32 v2, v2, v3, v4
	v_lshlrev_b32_e32 v3, 4, v1
	v_add_u32_e32 v10, 0x2000, v3
	v_lshrrev_b32_e32 v4, 7, v10
	s_movk_i32 s4, 0xe0
	s_waitcnt lgkmcnt(0)
	v_and_b32_e32 v6, 32, v1
	v_and_or_b32 v5, v4, s4, v2
	v_bitop3_b32 v11, v3, v6, 48 bitop3:0x6c
	v_and_b32_e32 v12, 64, v1
	v_bfe_u32 v13, v1, 2, 4
	s_movk_i32 s4, 0xf0
	v_or_b32_e32 v3, v11, v12
	v_and_or_b32 v4, v4, s4, v13
	s_add_u32 s3, s88, 0x200000
	v_lshl_or_b32 v132, v4, 11, v3
	v_lshrrev_b32_e32 v4, 3, v1
	s_movk_i32 s4, 0x60
	s_addc_u32 s33, s89, 0
	v_and_or_b32 v2, v4, s4, v2
	s_movk_i32 s4, 0x70
	s_ashr_i32 s43, s2, 31
	v_lshl_or_b32 v134, v2, 11, v3
	v_and_or_b32 v2, v4, s4, v13
	s_lshr_b32 s4, s43, 29
	s_add_i32 s4, s2, s4
	s_lshr_b32 s8, s5, 6
	s_ashr_i32 s6, s4, 3
	s_and_b32 s4, s4, -8
	s_lshr_b32 s9, s5, 8
	s_lshl_b32 s42, s8, 10
	s_sub_i32 s4, s2, s4
	s_cmp_lt_i32 s4, 0
	s_movk_i32 s44, 0x2ed
	s_cselect_b32 s7, s44, 0x2ec
	s_mul_i32 s4, s4, s7
	s_add_i32 s4, s4, s6
	s_mul_hi_i32 s6, s4, 0x2e8ba2e9
	s_lshr_b32 s7, s6, 31
	s_ashr_i32 s6, s6, 5
	s_add_i32 s6, s6, s7
	s_lshl_b32 s7, s6, 3
	s_mulk_i32 s6, 0xb0
	s_sub_i32 s6, s4, s6
	s_sext_i32_i16 s4, s6
	s_bfe_u32 s4, s4, 0x3001c
	s_add_i32 s12, s6, s4
	s_sext_i32_i16 s4, s12
	s_and_b32 s12, s12, 0xfff8
	s_sub_i32 s6, s6, s12
	s_sext_i32_i16 s6, s6
	s_lshr_b32 s4, s4, 3
	s_add_i32 s34, s7, s6
	s_ashr_i32 s35, s34, 31
	s_bfe_i64 s[12:13], s[4:5], 0x100000
	s_lshl_b64 s[6:7], s[34:35], 19
	s_lshl_b64 s[12:13], s[12:13], 19
	s_add_u32 s38, s3, s12
	s_addc_u32 s39, s33, s13
	s_add_i32 s35, s42, 0
	s_add_i32 m0, s35, 0x10000
	v_lshl_or_b32 v130, v5, 11, v3
	global_load_lds_dwordx4 v134, s[38:39]
	s_add_i32 m0, s35, 0x12000
	s_add_u32 s12, s38, 0x40000
	global_load_lds_dwordx4 v130, s[38:39]
	s_addc_u32 s13, s39, 0
	s_add_i32 m0, s35, 0x14000
	v_lshl_or_b32 v136, v2, 11, v3
	global_load_lds_dwordx4 v134, s[12:13]
	s_add_i32 m0, s35, 0x16000
	s_add_u32 s36, s60, s6
	s_addc_u32 s37, s61, s7
	s_add_i32 s45, s35, 0x2000
	global_load_lds_dwordx4 v130, s[12:13]
	s_mov_b32 m0, s35
	s_add_u32 s6, s36, 0x40000
	global_load_lds_dwordx4 v136, s[36:37]
	s_mov_b32 m0, s45
	s_addc_u32 s7, s37, 0
	s_add_i32 s46, s35, 0x4000
	global_load_lds_dwordx4 v132, s[36:37]
	s_mov_b32 m0, s46
	s_add_i32 s47, s35, 0x6000
	global_load_lds_dwordx4 v136, s[6:7]
	s_mov_b32 m0, s47
	v_mov_b32_e32 v135, 0
	global_load_lds_dwordx4 v132, s[6:7]
	v_mov_b32_e32 v131, v135
	v_mov_b32_e32 v137, v135
	v_mov_b32_e32 v133, v135
	s_cmp_eq_u32 s9, 1
	s_mov_b32 s48, 0
	v_lshl_add_u64 v[8:9], s[38:39], 0, v[134:135]
	v_lshl_add_u64 v[6:7], s[38:39], 0, v[130:131]
	v_lshl_add_u64 v[2:3], s[36:37], 0, v[136:137]
	s_cselect_b64 s[6:7], -1, 0
	s_cmp_lg_u32 s9, 1
	v_lshl_add_u64 v[4:5], s[36:37], 0, v[132:133]
	s_cbranch_scc1 .LBB0_286
	s_barrier

; #define SEAM(k) do { if (IN(k) && IN((k) + 1)) { if (a.ph_hi > 4096) cg::this_grid().sync(); else xcd_barrier(xbar); } } while (0)
;     __host__ __device__ bool next(int i, Unit& u) const {
;         const long L = (long)i * G + c; if (L >= nwg) return false;
;         int wgid = (int)L; { const int q = nwg / NXCD, r = nwg % NXCD, xcd = wgid % NXCD, off = wgid / NXCD; wgid = (xcd < r ? xcd * (q + 1) : r * (q + 1) + (xcd - r) * q) + off; }
;         const int nig = WGM * nN, gid = wgid / nig, fm = gid * WGM, gsz = (nM - fm) < WGM ? (nM - fm) : WGM;
;         u.pm = fm + ((wgid % nig) % gsz); u.pn = (wgid % nig) / gsz; return true;
; __global__ void __launch_bounds__(512, 2) fwd_kernel(Args a) {
;     ...
;     if (IN(5)) { pg8::Gemm g{XN, (const bf16_t*)(ws + WS_WIN), MALL, ZW, D}; pg8::StaticOrder S; S.init(MALL, ZW, G, (int)blockIdx.x); EpiZ E{ZH, (float*)(ws + WS_RSP), (const float*)(ws + WS_RS2), (const float*)(ws + WS_SHW1)};
;         pg8::gemm_phase<EpiZ, pg8::StaticOrder, true, true>(ldsg, g, S, E); } SEAM(5);
.LBB0_469:
	s_cmp_ge_u32 s2, 176
	s_cselect_b32 s100, 1700, 0
	s_memrealtime s[98:99]
	s_waitcnt lgkmcnt(0)
	s_add_u32 s100, s100, s98
.Lstag_p5:
	s_sleep 8
	s_memrealtime s[98:99]
	s_waitcnt lgkmcnt(0)
	s_sub_u32 s101, s100, s98
	s_cmp_gt_i32 s101, 0
	s_cbranch_scc1 .Lstag_p5
	s_cmp_lt_i32 s90, 6
	s_cselect_b64 s[0:1], -1, 0
	s_cmp_gt_i32 s91, 5
	s_cselect_b64 s[4:5], -1, 0
	s_and_b64 s[0:1], s[0:1], s[4:5]
	s_andn2_b64 vcc, exec, s[0:1]
	s_cbranch_vccnz .LBB0_1290
	s_cmpk_lt_i32 s2, 0xbb0
	s_cselect_b64 s[4:5], -1, 0
	s_cmpk_gt_i32 s2, 0xbaf
	v_readfirstlane_b32 s12, v1
	s_cbranch_scc1 .LBB0_472
	s_ashr_i32 s3, s2, 31
	s_lshr_b32 s3, s3, 29
	s_add_i32 s3, s2, s3
	s_ashr_i32 s6, s3, 3
	s_and_b32 s3, s3, -8
	s_sub_i32 s3, s2, s3
	s_cmp_lt_i32 s3, 0
	s_movk_i32 s7, 0x177
	s_cselect_b32 s7, s7, 0x176
	s_mul_i32 s3, s3, s7
	s_add_i32 s3, s3, s6
	s_mul_hi_i32 s6, s3, 0x2e8ba2e9
	s_lshr_b32 s7, s6, 31
	s_ashr_i32 s6, s6, 4
	s_add_i32 s6, s6, s7
	s_lshl_b32 s7, s6, 3
	s_mulk_i32 s6, 0x58
	s_sub_i32 s3, s3, s6
	s_bfe_i32 s6, s3, 0x80000
	s_bfe_u32 s6, s6, 0x3000c
	s_add_i32 s6, s3, s6
	s_bfe_i32 s8, s6, 0x80000
	s_and_b32 s6, s6, 0xf8
	s_sub_i32 s3, s3, s6
	s_sext_i32_i16 s8, s8
	s_sext_i32_i8 s3, s3
	s_add_i32 s6, s7, s3
	s_ashr_i32 s10, s8, 3

; #define PG8_WAIT_V(n) asm volatile("s_waitcnt vmcnt(" #n ")" ::: "memory")
; #define PG8_BAR __builtin_amdgcn_s_barrier()
; template <class Epi, class Sched, bool ALIGN_EPI = false, bool SP2 = false>
; __device__ __forceinline__ void gemm_phase(PG8_LAS unsigned char* lds, const Gemm g, const Sched& S, const Epi& E) {
;     const int tid = threadIdx.x, wid = __builtin_amdgcn_readfirstlane(tid >> 6), lane = tid & 63, wr = wid >> 2, wc = wid & 3, fr = lane & 15, fq = lane >> 4;
;     const int K = g.K, nt = K / BK;
;     unsigned voffA[2], voffB[2];
; #pragma unroll
;     for (int i = 0; i < 2; ++i) { int R, C; stage_rc(tid * 16 + i * 8192, R, C); const int Rb = Epi::PERM ? ((R & ~31) + perm32(R & 31)) : R;
;         voffA[i] = (unsigned)(R * K + C) * 2u; voffB[i] = (unsigned)(Rb * K + C) * 2u; }
;     const size_t kstep = (size_t)(BK * 2);
;     const size_t hstep = (size_t)HALF * K * 2;
;     const size_t tstep = 2 * hstep;
;     const unsigned ldsw = (unsigned)wid * 1024u;
;     const int aoff = lds_byte(wr * 64 + fr, fq * 8), boff = lds_byte(wc * 32 + fr, fq * 8);
;     ...
;     Unit cur, nxt; int ui = 0;
;     if (!S.next(0, cur)) return;
;     f32x4 acc[2][2][4][2];
; #pragma unroll
;     for (int a = 0; a < 2; ++a)
; #pragma unroll
;         for (int b = 0; b < 2; ++b)
; #pragma unroll
;             for (int m = 0; m < 4; ++m)
; #pragma unroll
;                 for (int n = 0; n < 2; ++n) acc[a][b][m][n] = (f32x4){0.f, 0.f, 0.f, 0.f};
;     bf16x8 At[4][2], B0[2][2], B1[2][2];
;     const char* cA = (const char*)g.A + (size_t)cur.pm * tstep; const char* cB = (const char*)g.Bt + (size_t)cur.pn * tstep;
;     S.a_ready(cur);
;     if constexpr (SP2) {
;         PG8_STAGE(PG8_SB(0, 0), cB, voffB); PG8_STAGE(PG8_SB(0, 1), cB + hstep, voffB); PG8_STAGE(PG8_SA(0, 0), cA, voffA); PG8_STAGE(PG8_SA(0, 1), cA + hstep, voffA);
;         if (wr == 1) PG8_BAR;
;         PG8_WAIT_V(2); PG8_BAR;
; __global__ void __launch_bounds__(512, 2) fwd_kernel(Args a) {
;     ...
;     if (IN(12)) { pg8::Gemm g{XN, (const bf16_t*)(ws + WS_W2A), MLAT, NFF2, D}; pg8::StaticOrder S; S.init(MLAT, NFF2, G, (int)blockIdx.x); EpiSwiGLU<true> E{ZH, (const float*)(ws + WS_RS3), (const float*)(ws + WS_SHW2)};
;         pg8::gemm_phase<EpiSwiGLU<true>, pg8::StaticOrder, true, true>(ldsg, g, S, E); } SEAM(12);
.LBB0_1885:
	s_lshr_b32 s100, s2, 7
	s_and_b32 s100, s100, 1
	s_mul_i32 s100, s100, 1200
	s_memrealtime s[98:99]
	s_waitcnt lgkmcnt(0)
	s_add_u32 s100, s100, s98
.Lstag_p12:
	s_sleep 8
	s_memrealtime s[98:99]
	s_waitcnt lgkmcnt(0)
	s_sub_u32 s101, s100, s98
	s_cmp_gt_i32 s101, 0
	s_cbranch_scc1 .Lstag_p12
	s_cmp_lt_i32 s90, 13
	s_cselect_b64 s[0:1], -1, 0
	s_cmp_gt_i32 s91, 12
	s_cselect_b64 s[4:5], -1, 0
	s_and_b64 s[8:9], s[0:1], s[4:5]
	s_andn2_b64 vcc, exec, s[8:9]
	s_cbranch_vccnz .LBB0_1902
	s_cmpk_gt_i32 s2, 0x15ff
	v_readfirstlane_b32 s5, v1
	s_cbranch_scc1 .LBB0_1902
	s_waitcnt vmcnt(0)
	v_lshrrev_b32_e32 v2, 5, v1
	v_lshrrev_b32_e32 v4, 1, v1
	v_and_b32_e32 v2, 4, v2
	s_waitcnt lgkmcnt(0)
	v_bfe_u32 v3, v1, 2, 2
	v_and_b32_e32 v4, 24, v4
	v_or3_b32 v2, v2, v3, v4
	v_lshlrev_b32_e32 v3, 4, v1
	v_add_u32_e32 v10, 0x2000, v3
	v_lshrrev_b32_e32 v4, 7, v10
	s_movk_i32 s0, 0xe0
	v_and_b32_e32 v6, 32, v1
	v_and_or_b32 v5, v4, s0, v2
	v_bitop3_b32 v11, v3, v6, 48 bitop3:0x6c
	v_and_b32_e32 v12, 64, v1
	v_bfe_u32 v13, v1, 2, 4
	s_movk_i32 s0, 0xf0
	v_or_b32_e32 v3, v11, v12
	v_and_or_b32 v4, v4, s0, v13
	s_add_u32 s3, s88, 0x1b00000
	v_lshl_or_b32 v150, v4, 11, v3
	v_lshrrev_b32_e32 v4, 3, v1
	s_movk_i32 s0, 0x60
	s_addc_u32 s19, s89, 0
	v_and_or_b32 v2, v4, s0, v2
	s_movk_i32 s0, 0x70
	s_ashr_i32 s33, s2, 31
	v_lshl_or_b32 v152, v2, 11, v3
	v_and_or_b32 v2, v4, s0, v13
	s_lshr_b32 s0, s33, 29
	s_add_i32 s0, s2, s0
	s_lshr_b32 s14, s5, 6
	s_ashr_i32 s1, s0, 3
	s_and_b32 s0, s0, -8
	s_lshr_b32 s15, s5, 8
	s_lshl_b32 s21, s14, 10
	s_sub_i32 s0, s2, s0
	s_cmp_lt_i32 s0, 0
	s_movk_i32 s36, 0x2c1
	s_cselect_b32 s4, s36, 0x2c0
	s_mul_i32 s0, s0, s4
	s_add_i32 s0, s0, s1
	s_mul_hi_i32 s1, s0, 0x2e8ba2e9
	s_lshr_b32 s4, s1, 31
	s_ashr_i32 s1, s1, 5
	s_add_i32 s1, s1, s4
	s_lshl_b32 s6, s1, 3
	s_mulk_i32 s1, 0xb0
	s_sub_i32 s0, s0, s1
	s_sext_i32_i16 s1, s0
	s_bfe_u32 s1, s1, 0x3001c
	s_add_i32 s1, s0, s1
	s_sext_i32_i16 s4, s1
	s_and_b32 s1, s1, 0xfff8
	s_sub_i32 s0, s0, s1
	s_sext_i32_i16 s0, s0
	s_lshr_b32 s4, s4, 3
	s_add_i32 s0, s6, s0
	s_ashr_i32 s1, s0, 31
	s_bfe_i64 s[10:11], s[4:5], 0x100000
	s_lshl_b64 s[6:7], s[0:1], 19
	s_lshl_b64 s[10:11], s[10:11], 19
	s_add_u32 s30, s3, s10
	s_addc_u32 s31, s19, s11
	s_add_i32 s37, s21, 0
	s_add_i32 m0, s37, 0x10000
	v_lshl_or_b32 v148, v5, 11, v3
	global_load_lds_dwordx4 v152, s[30:31]
	s_add_i32 m0, s37, 0x12000
	s_add_u32 s10, s30, 0x40000
	global_load_lds_dwordx4 v148, s[30:31]
	s_addc_u32 s11, s31, 0
	s_add_i32 m0, s37, 0x14000
	v_lshl_or_b32 v154, v2, 11, v3
	global_load_lds_dwordx4 v152, s[10:11]
	s_add_i32 m0, s37, 0x16000
	s_add_u32 s6, s60, s6
	s_addc_u32 s7, s61, s7
	s_add_i32 s38, s37, 0x2000
	global_load_lds_dwordx4 v148, s[10:11]
	s_mov_b32 m0, s37
	s_add_u32 s10, s6, 0x40000
	global_load_lds_dwordx4 v154, s[6:7]
	s_mov_b32 m0, s38
	s_addc_u32 s11, s7, 0
	s_add_i32 s39, s37, 0x4000
	global_load_lds_dwordx4 v150, s[6:7]
	s_mov_b32 m0, s39
	s_add_i32 s40, s37, 0x6000
	global_load_lds_dwordx4 v154, s[10:11]
	s_mov_b32 m0, s40
	v_mov_b32_e32 v153, 0
	global_load_lds_dwordx4 v150, s[10:11]
	v_mov_b32_e32 v149, v153
	v_mov_b32_e32 v155, v153
	v_mov_b32_e32 v151, v153
	s_cmp_eq_u32 s15, 1
	s_mov_b32 s41, 0
	v_lshl_add_u64 v[8:9], s[30:31], 0, v[152:153]
	v_lshl_add_u64 v[6:7], s[30:31], 0, v[148:149]
	v_lshl_add_u64 v[2:3], s[6:7], 0, v[154:155]
	s_cselect_b64 s[10:11], -1, 0
	s_cmp_lg_u32 s15, 1
	v_lshl_add_u64 v[4:5], s[6:7], 0, v[150:151]
	s_cbranch_scc1 .LBB0_1889
	s_barrier
